# LN0->MLA G1 and LN1->NA G1 grid barriers replaced by team syncs (second per-team counter, L1 invalidate after acquire)
# speedup vs baseline: 1.0232x; 1.0042x over previous
.LBB0_555:
	s_or_b64 exec, exec, s[8:9]
	v_lshrrev_b32_e32 v2, 11, v12
	v_mad_u32_u24 v2, v2, s42, v11
	v_cndmask_b32_e64 v12, v2, v102, s[4:5]
	v_lshl_add_u64 v[2:3], v[12:13], 2, s[16:17]
	v_lshrrev_b32_e32 v4, 11, v35
	v_mad_u32_u24 v4, v4, s42, v11
	v_lshl_add_u64 v[76:77], v[2:3], 0, s[38:39]
	v_mov_b32_e32 v35, v13
	v_cndmask_b32_e64 v12, v4, v102, s[6:7]
	v_lshl_add_u64 v[4:5], v[76:77], 0, v[34:35]
	global_load_dwordx4 v[104:107], v[4:5], off
	v_lshl_add_u64 v[80:81], v[2:3], 0, v[34:35]
	global_load_dwordx4 v[108:111], v[80:81], off
	v_lshl_add_u64 v[6:7], v[12:13], 2, s[16:17]
	v_lshl_add_u64 v[84:85], v[6:7], 0, s[38:39]
	v_lshl_add_u64 v[2:3], v[84:85], 0, v[34:35]
	v_lshl_add_u64 v[82:83], v[6:7], 0, v[34:35]
	global_load_dwordx4 v[6:9], v[82:83], off
	v_lshl_add_u64 v[78:79], v[32:33], 0, v[22:23]
	global_load_dwordx4 v[2:5], v[2:3], off
	s_waitcnt vmcnt(3)
	v_pk_add_f32 v[104:105], v[104:105], 1.0 op_sel_hi:[1,0]
	v_pk_add_f32 v[106:107], v[106:107], 1.0 op_sel_hi:[1,0]
	s_waitcnt vmcnt(2)
	v_pk_fma_f32 v[74:75], v[74:75], v[104:105], v[108:109]
	v_pk_fma_f32 v[94:95], v[94:95], v[106:107], v[110:111]
	v_cvt_pk_bf16_f32 v74, v74, v75
	v_cvt_pk_bf16_f32 v75, v94, v95
	global_store_dwordx2 v[78:79], v[74:75], off sc1
	v_lshl_add_u64 v[74:75], v[28:29], 0, v[22:23]
	s_and_saveexec_b64 s[4:5], vcc
	s_cbranch_execz .LBB0_557
	s_waitcnt vmcnt(1)
	v_pk_add_f32 v[4:5], v[4:5], 1.0 op_sel_hi:[1,0]
	v_pk_add_f32 v[2:3], v[2:3], 1.0 op_sel_hi:[1,0]
	v_pk_fma_f32 v[4:5], v[92:93], v[4:5], v[8:9]
	v_pk_fma_f32 v[2:3], v[90:91], v[2:3], v[6:7]
	v_cvt_pk_bf16_f32 v5, v4, v5
	v_cvt_pk_bf16_f32 v4, v2, v3
	global_store_dwordx2 v[74:75], v[4:5], off sc1

.LBB0_559:
	s_or_b64 exec, exec, s[4:5]
	v_mov_b32_e32 v41, v13
	v_lshl_add_u64 v[2:3], v[76:77], 0, v[40:41]
	global_load_dwordx4 v[90:93], v[2:3], off
	global_load_dwordx4 v[104:107], v[80:81], off offset:1024
	v_lshl_add_u64 v[94:95], v[84:85], 0, v[40:41]
	global_load_dwordx4 v[6:9], v[94:95], off
	global_load_dwordx4 v[2:5], v[82:83], off offset:1024
	s_waitcnt vmcnt(3)
	v_pk_add_f32 v[90:91], v[90:91], 1.0 op_sel_hi:[1,0]
	v_pk_add_f32 v[92:93], v[92:93], 1.0 op_sel_hi:[1,0]
	s_waitcnt vmcnt(2)
	v_pk_fma_f32 v[86:87], v[86:87], v[90:91], v[104:105]
	v_pk_fma_f32 v[88:89], v[88:89], v[92:93], v[106:107]
	v_cvt_pk_bf16_f32 v86, v86, v87
	v_cvt_pk_bf16_f32 v87, v88, v89
	global_store_dwordx2 v[78:79], v[86:87], off offset:512 sc1
	s_and_saveexec_b64 s[4:5], vcc
	s_cbranch_execz .LBB0_561
	s_waitcnt vmcnt(2)
	v_pk_add_f32 v[8:9], v[8:9], 1.0 op_sel_hi:[1,0]
	v_pk_add_f32 v[6:7], v[6:7], 1.0 op_sel_hi:[1,0]
	s_waitcnt vmcnt(1)
	v_pk_fma_f32 v[4:5], v[60:61], v[8:9], v[4:5]
	v_pk_fma_f32 v[2:3], v[58:59], v[6:7], v[2:3]
	v_cvt_pk_bf16_f32 v5, v4, v5
	v_cvt_pk_bf16_f32 v4, v2, v3
	global_store_dwordx2 v[74:75], v[4:5], off offset:512 sc1

.LBB0_563:
	s_or_b64 exec, exec, s[4:5]
	v_mov_b32_e32 v43, v13
	v_lshl_add_u64 v[2:3], v[76:77], 0, v[42:43]
	global_load_dwordx4 v[70:73], v[2:3], off
	global_load_dwordx4 v[86:89], v[80:81], off offset:2048
	v_lshl_add_u64 v[90:91], v[84:85], 0, v[42:43]
	global_load_dwordx4 v[6:9], v[90:91], off
	global_load_dwordx4 v[2:5], v[82:83], off offset:2048
	s_waitcnt vmcnt(3)
	v_pk_add_f32 v[70:71], v[70:71], 1.0 op_sel_hi:[1,0]
	v_pk_add_f32 v[72:73], v[72:73], 1.0 op_sel_hi:[1,0]
	s_waitcnt vmcnt(2)
	v_pk_fma_f32 v[58:59], v[58:59], v[70:71], v[86:87]
	v_pk_fma_f32 v[60:61], v[60:61], v[72:73], v[88:89]
	v_cvt_pk_bf16_f32 v58, v58, v59
	v_cvt_pk_bf16_f32 v59, v60, v61
	global_store_dwordx2 v[78:79], v[58:59], off offset:1024 sc1
	s_and_saveexec_b64 s[4:5], vcc
	s_cbranch_execz .LBB0_565
	s_waitcnt vmcnt(2)
	v_pk_add_f32 v[8:9], v[8:9], 1.0 op_sel_hi:[1,0]
	v_pk_add_f32 v[6:7], v[6:7], 1.0 op_sel_hi:[1,0]
	s_waitcnt vmcnt(1)
	v_pk_fma_f32 v[4:5], v[56:57], v[8:9], v[4:5]
	v_pk_fma_f32 v[2:3], v[54:55], v[6:7], v[2:3]
	v_cvt_pk_bf16_f32 v5, v4, v5
	v_cvt_pk_bf16_f32 v4, v2, v3
	global_store_dwordx2 v[74:75], v[4:5], off offset:1024 sc1

.LBB0_567:
	s_or_b64 exec, exec, s[4:5]
	v_mov_b32_e32 v45, v13
	v_lshl_add_u64 v[2:3], v[76:77], 0, v[44:45]
	global_load_dwordx4 v[54:57], v[2:3], off
	global_load_dwordx4 v[58:61], v[80:81], off offset:3072
	v_lshl_add_u64 v[62:63], v[84:85], 0, v[44:45]
	global_load_dwordx4 v[6:9], v[62:63], off
	global_load_dwordx4 v[2:5], v[82:83], off offset:3072
	s_waitcnt vmcnt(3)
	v_pk_add_f32 v[54:55], v[54:55], 1.0 op_sel_hi:[1,0]
	v_pk_add_f32 v[56:57], v[56:57], 1.0 op_sel_hi:[1,0]
	s_waitcnt vmcnt(2)
	v_pk_fma_f32 v[50:51], v[50:51], v[54:55], v[58:59]
	v_pk_fma_f32 v[52:53], v[52:53], v[56:57], v[60:61]
	v_cvt_pk_bf16_f32 v50, v50, v51
	v_cvt_pk_bf16_f32 v51, v52, v53
	global_store_dwordx2 v[78:79], v[50:51], off offset:1536 sc1
	s_and_saveexec_b64 s[4:5], vcc
	s_cbranch_execz .LBB0_548
	s_waitcnt vmcnt(2)
	v_pk_add_f32 v[8:9], v[8:9], 1.0 op_sel_hi:[1,0]
	v_pk_add_f32 v[6:7], v[6:7], 1.0 op_sel_hi:[1,0]
	s_waitcnt vmcnt(1)
	v_pk_fma_f32 v[4:5], v[48:49], v[8:9], v[4:5]
	v_pk_fma_f32 v[2:3], v[46:47], v[6:7], v[2:3]
	v_cvt_pk_bf16_f32 v5, v4, v5
	v_cvt_pk_bf16_f32 v4, v2, v3
	global_store_dwordx2 v[74:75], v[4:5], off offset:1536 sc1
	s_branch .LBB0_548
.LBB0_569:
	s_or_b64 exec, exec, s[24:25]
	s_load_dword s66, s[0:1], 0x468
	s_waitcnt lgkmcnt(0)
	s_cmpk_lg_u32 s66, 0x200
	s_cbranch_scc1 FUSE6_ORIG
	s_cmp_lt_i32 s23, 8
	s_cbranch_scc1 FUSE6_ORIG
	s_waitcnt vmcnt(0)
	s_barrier
	v_bfe_u32 v5, v0, 6, 2
	s_and_b32 s73, s2, 0x1ff
	s_nop 1
	v_readfirstlane_b32 s67, v5
	s_cmp_lg_u32 s67, 0
	s_cbranch_scc1 FUSE6_WAIT
	s_and_b32 s67, s73, 63
	s_lshl_b32 s68, s67, 6
	s_and_b32 s69, s67, 32
	s_lshl_b32 s69, s69, 6
	s_add_u32 s68, s68, s69
	s_add_u32 s68, s68, 0x1c20
	v_mov_b32_e32 v2, s68
	v_mov_b32_e32 v3, 1
	s_mov_b64 s[70:71], exec
	s_mov_b64 exec, 1
	s_mov_b32 s74, 0
	global_atomic_add v2, v3, s[20:21]
FUSE6_SPIN:
	global_load_dword v4, v2, s[20:21] sc1
	s_waitcnt vmcnt(0)
	v_readfirstlane_b32 s69, v4
	s_cmp_ge_u32 s69, 8
	s_cbranch_scc1 FUSE6_GOT
	s_add_i32 s74, s74, 1
	s_cmp_gt_u32 s74, 0x100000
	s_cbranch_scc1 FUSE6_GOT
	s_sleep 1
	s_branch FUSE6_SPIN
FUSE6_GOT:
	s_mov_b64 exec, s[70:71]
	buffer_inv sc1
	s_waitcnt vmcnt(0)
FUSE6_WAIT:
	s_barrier
	s_branch .LBB0_622
FUSE6_ORIG:
	s_cmp_lt_i32 s23, 8
	s_cbranch_scc1 .LBB0_622
	s_waitcnt vmcnt(0)
	v_cmp_eq_u32_e32 vcc, 0, v39
	s_waitcnt vmcnt(0)
	v_mov_b32_e32 v2, v146
	v_mov_b32_e32 v4, v148
	s_waitcnt lgkmcnt(0)
	s_barrier
	s_and_saveexec_b64 s[4:5], vcc
	s_cbranch_execz .LBB0_619
	v_cmp_eq_u32_e32 vcc, 0, v148
	v_mov_b32_e32 v2, v146
	v_mov_b32_e32 v4, v148
	s_waitcnt vmcnt(0) expcnt(0) lgkmcnt(0)
	s_and_saveexec_b64 s[6:7], vcc
	s_cbranch_execz .LBB0_586
	s_load_dwordx2 s[12:13], s[10:11], 0x4
	s_add_u32 s8, s20, 0x1000
	s_addc_u32 s9, s21, 0
	s_add_u32 s10, s20, 0x1100
	s_addc_u32 s11, s21, 0
	s_waitcnt lgkmcnt(0)
	s_mul_i32 s3, s12, s3
	s_add_u32 s12, s20, 0x1200
	s_mul_i32 s3, s3, s13
	s_addc_u32 s13, s21, 0
	s_add_u32 s14, s20, 0x1300
	s_addc_u32 s15, s21, 0
	s_mov_b32 s26, 1
	v_mov_b32_e32 v18, 0
	s_branch .LBB0_574

.LBB0_1195:
	s_or_b64 exec, exec, s[4:5]
	v_add_u32_e32 v3, 0xfffff000, v10
	v_lshrrev_b32_e32 v3, 11, v3
	v_mad_u32_u24 v3, v3, s28, v11
	v_cmp_lt_i32_e64 s[4:5], s29, v10
	v_mov_b32_e32 v49, v13
	v_lshl_add_u64 v[88:89], v[44:45], 0, v[34:35]
	v_cndmask_b32_e64 v12, v112, v3, s[4:5]
	v_add_u32_e32 v3, 0xfffff000, v2
	v_lshl_add_u64 v[4:5], v[12:13], 2, s[8:9]
	v_lshrrev_b32_e32 v3, 11, v3
	v_mad_u32_u24 v3, v3, s28, v11
	v_cmp_lt_i32_e64 s[4:5], s29, v2
	v_lshl_add_u64 v[86:87], v[4:5], 0, s[14:15]
	v_lshl_add_u64 v[90:91], v[4:5], 0, v[48:49]
	v_cndmask_b32_e64 v12, v112, v3, s[4:5]
	v_lshl_add_u64 v[2:3], v[86:87], 0, v[48:49]
	global_load_dwordx4 v[114:117], v[2:3], off
	global_load_dwordx4 v[118:121], v[90:91], off
	v_lshl_add_u64 v[6:7], v[12:13], 2, s[8:9]
	v_lshl_add_u64 v[92:93], v[6:7], 0, s[14:15]
	v_lshl_add_u64 v[2:3], v[92:93], 0, v[48:49]
	v_lshl_add_u64 v[94:95], v[6:7], 0, v[48:49]
	global_load_dwordx4 v[2:5], v[2:3], off
	s_waitcnt vmcnt(2)
	v_pk_add_f32 v[114:115], v[114:115], 1.0 op_sel_hi:[1,0]
	global_load_dwordx4 v[6:9], v[94:95], off
	v_pk_add_f32 v[116:117], v[116:117], 1.0 op_sel_hi:[1,0]
	s_waitcnt vmcnt(2)
	v_pk_fma_f32 v[84:85], v[84:85], v[114:115], v[118:119]
	v_pk_fma_f32 v[104:105], v[104:105], v[116:117], v[120:121]
	v_cvt_pk_bf16_f32 v84, v84, v85
	v_cvt_pk_bf16_f32 v85, v104, v105
	global_store_dwordx2 v[88:89], v[84:85], off sc1
	v_lshl_add_u64 v[84:85], v[42:43], 0, v[34:35]
	s_and_saveexec_b64 s[4:5], vcc
	s_cbranch_execz .LBB0_1197
	s_waitcnt vmcnt(2)
	v_pk_add_f32 v[4:5], v[4:5], 1.0 op_sel_hi:[1,0]
	v_pk_add_f32 v[2:3], v[2:3], 1.0 op_sel_hi:[1,0]
	s_waitcnt vmcnt(1)
	v_pk_fma_f32 v[4:5], v[102:103], v[4:5], v[8:9]
	v_pk_fma_f32 v[2:3], v[100:101], v[2:3], v[6:7]
	v_cvt_pk_bf16_f32 v5, v4, v5
	v_cvt_pk_bf16_f32 v4, v2, v3
	global_store_dwordx2 v[84:85], v[4:5], off sc1

.LBB0_1199:
	s_or_b64 exec, exec, s[4:5]
	v_mov_b32_e32 v51, v13
	v_lshl_add_u64 v[2:3], v[86:87], 0, v[50:51]
	global_load_dwordx4 v[100:103], v[2:3], off
	global_load_dwordx4 v[114:117], v[90:91], off offset:1024
	v_lshl_add_u64 v[104:105], v[92:93], 0, v[50:51]
	global_load_dwordx4 v[6:9], v[104:105], off
	global_load_dwordx4 v[2:5], v[94:95], off offset:1024
	s_waitcnt vmcnt(3)
	v_pk_add_f32 v[100:101], v[100:101], 1.0 op_sel_hi:[1,0]
	v_pk_add_f32 v[102:103], v[102:103], 1.0 op_sel_hi:[1,0]
	s_waitcnt vmcnt(2)
	v_pk_fma_f32 v[96:97], v[96:97], v[100:101], v[114:115]
	v_pk_fma_f32 v[98:99], v[98:99], v[102:103], v[116:117]
	v_cvt_pk_bf16_f32 v96, v96, v97
	v_cvt_pk_bf16_f32 v97, v98, v99
	global_store_dwordx2 v[88:89], v[96:97], off offset:512 sc1
	s_and_saveexec_b64 s[4:5], vcc
	s_cbranch_execz .LBB0_1201
	s_waitcnt vmcnt(2)
	v_pk_add_f32 v[8:9], v[8:9], 1.0 op_sel_hi:[1,0]
	v_pk_add_f32 v[6:7], v[6:7], 1.0 op_sel_hi:[1,0]
	s_waitcnt vmcnt(1)
	v_pk_fma_f32 v[4:5], v[72:73], v[8:9], v[4:5]
	v_pk_fma_f32 v[2:3], v[70:71], v[6:7], v[2:3]
	v_cvt_pk_bf16_f32 v5, v4, v5
	v_cvt_pk_bf16_f32 v4, v2, v3
	global_store_dwordx2 v[84:85], v[4:5], off offset:512 sc1

.LBB0_1203:
	s_or_b64 exec, exec, s[4:5]
	v_mov_b32_e32 v53, v13
	v_lshl_add_u64 v[2:3], v[86:87], 0, v[52:53]
	global_load_dwordx4 v[80:83], v[2:3], off
	global_load_dwordx4 v[96:99], v[90:91], off offset:2048
	v_lshl_add_u64 v[100:101], v[92:93], 0, v[52:53]
	global_load_dwordx4 v[6:9], v[100:101], off
	global_load_dwordx4 v[2:5], v[94:95], off offset:2048
	s_waitcnt vmcnt(3)
	v_pk_add_f32 v[80:81], v[80:81], 1.0 op_sel_hi:[1,0]
	v_pk_add_f32 v[82:83], v[82:83], 1.0 op_sel_hi:[1,0]
	s_waitcnt vmcnt(2)
	v_pk_fma_f32 v[70:71], v[70:71], v[80:81], v[96:97]
	v_pk_fma_f32 v[72:73], v[72:73], v[82:83], v[98:99]
	v_cvt_pk_bf16_f32 v70, v70, v71
	v_cvt_pk_bf16_f32 v71, v72, v73
	global_store_dwordx2 v[88:89], v[70:71], off offset:1024 sc1
	s_and_saveexec_b64 s[4:5], vcc
	s_cbranch_execz .LBB0_1205
	s_waitcnt vmcnt(2)
	v_pk_add_f32 v[8:9], v[8:9], 1.0 op_sel_hi:[1,0]
	v_pk_add_f32 v[6:7], v[6:7], 1.0 op_sel_hi:[1,0]
	s_waitcnt vmcnt(1)
	v_pk_fma_f32 v[4:5], v[68:69], v[8:9], v[4:5]
	v_pk_fma_f32 v[2:3], v[66:67], v[6:7], v[2:3]
	v_cvt_pk_bf16_f32 v5, v4, v5
	v_cvt_pk_bf16_f32 v4, v2, v3
	global_store_dwordx2 v[84:85], v[4:5], off offset:1024 sc1

.LBB0_1207:
	s_or_b64 exec, exec, s[4:5]
	v_mov_b32_e32 v55, v13
	v_lshl_add_u64 v[2:3], v[86:87], 0, v[54:55]
	global_load_dwordx4 v[66:69], v[2:3], off
	global_load_dwordx4 v[70:73], v[90:91], off offset:3072
	v_lshl_add_u64 v[56:57], v[92:93], 0, v[54:55]
	global_load_dwordx4 v[6:9], v[56:57], off
	global_load_dwordx4 v[2:5], v[94:95], off offset:3072
	s_waitcnt vmcnt(3)
	v_pk_add_f32 v[56:57], v[66:67], 1.0 op_sel_hi:[1,0]
	v_pk_add_f32 v[66:67], v[68:69], 1.0 op_sel_hi:[1,0]
	s_waitcnt vmcnt(2)
	v_pk_fma_f32 v[56:57], v[62:63], v[56:57], v[70:71]
	v_pk_fma_f32 v[62:63], v[64:65], v[66:67], v[72:73]
	v_cvt_pk_bf16_f32 v56, v56, v57
	v_cvt_pk_bf16_f32 v57, v62, v63
	global_store_dwordx2 v[88:89], v[56:57], off offset:1536 sc1
	s_and_saveexec_b64 s[4:5], vcc
	s_cbranch_execz .LBB0_1192
	s_waitcnt vmcnt(2)
	v_pk_add_f32 v[8:9], v[8:9], 1.0 op_sel_hi:[1,0]
	v_pk_add_f32 v[6:7], v[6:7], 1.0 op_sel_hi:[1,0]
	s_waitcnt vmcnt(1)
	v_pk_fma_f32 v[4:5], v[60:61], v[8:9], v[4:5]
	v_pk_fma_f32 v[2:3], v[58:59], v[6:7], v[2:3]
	v_cvt_pk_bf16_f32 v5, v4, v5
	v_cvt_pk_bf16_f32 v4, v2, v3
	global_store_dwordx2 v[84:85], v[4:5], off offset:1536 sc1
	s_branch .LBB0_1192
.LBB0_1209:
	s_or_b64 exec, exec, s[12:13]
	s_load_dword s66, s[0:1], 0x468
	s_waitcnt lgkmcnt(0)
	s_cmpk_lg_u32 s66, 0x200
	s_cbranch_scc1 FUSE12_ORIG
	s_cmp_lt_i32 s23, 14
	s_cbranch_scc1 FUSE12_ORIG
	s_waitcnt vmcnt(0)
	s_barrier
	v_bfe_u32 v5, v0, 6, 2
	s_and_b32 s73, s2, 0x1ff
	s_nop 1
	v_readfirstlane_b32 s67, v5
	s_cmp_lg_u32 s67, 0
	s_cbranch_scc1 FUSE12_WAIT
	s_and_b32 s67, s73, 63
	s_lshl_b32 s68, s67, 6
	s_and_b32 s69, s67, 32
	s_lshl_b32 s69, s69, 6
	s_add_u32 s68, s68, s69
	s_add_u32 s68, s68, 0x1c20
	v_mov_b32_e32 v2, s68
	v_mov_b32_e32 v3, 1
	s_mov_b64 s[70:71], exec
	s_mov_b64 exec, 1
	s_mov_b32 s74, 0
	global_atomic_add v2, v3, s[20:21]
FUSE12_SPIN:
	global_load_dword v4, v2, s[20:21] sc1
	s_waitcnt vmcnt(0)
	v_readfirstlane_b32 s69, v4
	s_cmp_ge_u32 s69, 16
	s_cbranch_scc1 FUSE12_GOT
	s_add_i32 s74, s74, 1
	s_cmp_gt_u32 s74, 0x100000
	s_cbranch_scc1 FUSE12_GOT
	s_sleep 1
	s_branch FUSE12_SPIN
FUSE12_GOT:
	s_mov_b64 exec, s[70:71]
	buffer_inv sc1
	s_waitcnt vmcnt(0)
FUSE12_WAIT:
	s_barrier
	s_branch .LBB0_1262
FUSE12_ORIG:
	s_cmp_lt_i32 s23, 14
	s_cbranch_scc1 .LBB0_1262
	s_waitcnt vmcnt(0)
	v_cmp_eq_u32_e32 vcc, 0, v47
	s_waitcnt vmcnt(0)
	v_mov_b32_e32 v2, v146
	v_mov_b32_e32 v4, v148
	s_waitcnt lgkmcnt(0)
	s_barrier
	s_and_saveexec_b64 s[4:5], vcc
	s_cbranch_execz .LBB0_1259
	v_cmp_eq_u32_e32 vcc, 0, v148
	v_mov_b32_e32 v2, v146
	v_mov_b32_e32 v4, v148
	s_waitcnt vmcnt(0) expcnt(0) lgkmcnt(0)
	s_and_saveexec_b64 s[8:9], vcc
	s_cbranch_execz .LBB0_1226
	s_load_dwordx2 s[12:13], s[6:7], 0x4
	s_add_u32 s6, s20, 0x1000
	s_addc_u32 s7, s21, 0
	s_add_u32 s10, s20, 0x1100
	s_addc_u32 s11, s21, 0
	s_waitcnt lgkmcnt(0)
	s_mul_i32 s3, s12, s3
	s_add_u32 s12, s20, 0x1200
	s_mul_i32 s3, s3, s13
	s_addc_u32 s13, s21, 0
	s_add_u32 s14, s20, 0x1300
	s_addc_u32 s15, s21, 0
	s_mov_b32 s26, 1
	v_mov_b32_e32 v18, 0
	s_branch .LBB0_1214
